# filter generation (kcgen): per-channel 64-lane sum via DPP row adds + readlane instead of ds_bpermute butterfly
# baseline (speedup 1.0000x reference)
.LBB0_93:
	s_lshl_b32 s0, s29, 8
	s_add_i32 s0, s0, 0
	v_mov_b32_e32 v89, s0
	s_waitcnt lgkmcnt(0)
	ds_read_b128 v[90:93], v89
	ds_read_b128 v[94:97], v89 offset:16384
	ds_read_b128 v[98:101], v89 offset:16
	ds_read_b128 v[102:105], v89 offset:16400
	s_add_i32 s12, s29, s26
	s_waitcnt lgkmcnt(3)
	v_fma_f32 v106, v0, v90, 0
	s_waitcnt lgkmcnt(2)
	v_fma_f32 v107, v0, v94, 0
	v_fmac_f32_e32 v106, v1, v91
	v_fmac_f32_e32 v106, v2, v92
	v_fmac_f32_e32 v107, v1, v95
	v_fmac_f32_e32 v106, v3, v93
	v_fmac_f32_e32 v107, v2, v96
	v_fmac_f32_e32 v107, v3, v97
	s_waitcnt lgkmcnt(1)
	v_fmac_f32_e32 v106, v4, v98
	ds_read_b128 v[90:93], v89 offset:32
	ds_read_b128 v[94:97], v89 offset:48
	v_fmac_f32_e32 v106, v5, v99
	v_fmac_f32_e32 v106, v6, v100
	v_fmac_f32_e32 v106, v7, v101
	s_waitcnt lgkmcnt(1)
	v_fmac_f32_e32 v106, v8, v90
	v_fmac_f32_e32 v106, v9, v91
	ds_read_b128 v[98:101], v89 offset:16416
	v_fmac_f32_e32 v106, v10, v92
	v_fmac_f32_e32 v107, v4, v102
	v_fmac_f32_e32 v106, v11, v93
	v_fmac_f32_e32 v107, v5, v103
	s_waitcnt lgkmcnt(1)
	v_fmac_f32_e32 v106, v12, v94
	v_fmac_f32_e32 v107, v6, v104
	v_fmac_f32_e32 v106, v13, v95
	v_fmac_f32_e32 v107, v7, v105
	ds_read_b128 v[90:93], v89 offset:16432
	v_fmac_f32_e32 v106, v14, v96
	v_fmac_f32_e32 v106, v15, v97
	ds_read_b128 v[94:97], v89 offset:64
	s_waitcnt lgkmcnt(2)
	v_fmac_f32_e32 v107, v8, v98
	v_fmac_f32_e32 v107, v9, v99
	v_fmac_f32_e32 v107, v10, v100
	v_fmac_f32_e32 v107, v11, v101
	s_waitcnt lgkmcnt(1)
	v_fmac_f32_e32 v107, v12, v90
	v_fmac_f32_e32 v107, v13, v91
	v_fmac_f32_e32 v107, v14, v92
	v_fmac_f32_e32 v107, v15, v93
	ds_read_b128 v[90:93], v89 offset:16448
	ds_read_b128 v[98:101], v89 offset:80
	s_waitcnt lgkmcnt(2)
	v_fmac_f32_e32 v106, v16, v94
	v_fmac_f32_e32 v106, v17, v95
	v_fmac_f32_e32 v106, v18, v96
	v_fmac_f32_e32 v106, v19, v97
	ds_read_b128 v[94:97], v89 offset:16464
	s_waitcnt lgkmcnt(2)
	v_fmac_f32_e32 v107, v16, v90
	v_fmac_f32_e32 v107, v17, v91
	v_fmac_f32_e32 v107, v18, v92
	v_fmac_f32_e32 v107, v19, v93
	ds_read_b128 v[90:93], v89 offset:96
	s_waitcnt lgkmcnt(2)
	v_fmac_f32_e32 v106, v20, v98
	v_fmac_f32_e32 v106, v21, v99
	s_waitcnt lgkmcnt(1)
	v_fmac_f32_e32 v107, v20, v94
	v_fmac_f32_e32 v106, v22, v100
	v_fmac_f32_e32 v107, v21, v95
	v_fmac_f32_e32 v106, v23, v101
	v_fmac_f32_e32 v107, v22, v96
	v_fmac_f32_e32 v107, v23, v97
	ds_read_b128 v[94:97], v89 offset:16480
	ds_read_b128 v[98:101], v89 offset:112
	s_waitcnt lgkmcnt(2)
	v_fmac_f32_e32 v106, v24, v90
	v_fmac_f32_e32 v106, v25, v91
	v_fmac_f32_e32 v106, v26, v92
	v_fmac_f32_e32 v106, v27, v93
	ds_read_b128 v[90:93], v89 offset:16496
	s_waitcnt lgkmcnt(2)
	v_fmac_f32_e32 v107, v24, v94
	v_fmac_f32_e32 v107, v25, v95
	v_fmac_f32_e32 v107, v26, v96
	v_fmac_f32_e32 v107, v27, v97
	ds_read_b128 v[94:97], v89 offset:128
	s_waitcnt lgkmcnt(2)
	v_fmac_f32_e32 v106, v28, v98
	s_waitcnt lgkmcnt(1)
	v_fmac_f32_e32 v107, v28, v90
	v_fmac_f32_e32 v106, v29, v99
	v_fmac_f32_e32 v107, v29, v91
	v_fmac_f32_e32 v106, v30, v100
	v_fmac_f32_e32 v107, v30, v92
	v_fmac_f32_e32 v106, v31, v101
	v_fmac_f32_e32 v107, v31, v93
	ds_read_b128 v[90:93], v89 offset:16512
	ds_read_b128 v[98:101], v89 offset:144
	s_waitcnt lgkmcnt(2)
	v_fmac_f32_e32 v106, v32, v94
	v_fmac_f32_e32 v106, v33, v95
	v_fmac_f32_e32 v106, v34, v96
	v_fmac_f32_e32 v106, v35, v97
	ds_read_b128 v[94:97], v89 offset:16528
	s_waitcnt lgkmcnt(2)
	v_fmac_f32_e32 v107, v32, v90
	v_fmac_f32_e32 v107, v33, v91
	v_fmac_f32_e32 v107, v34, v92
	v_fmac_f32_e32 v107, v35, v93
	ds_read_b128 v[90:93], v89 offset:160
	s_waitcnt lgkmcnt(2)
	v_fmac_f32_e32 v106, v36, v98
	v_fmac_f32_e32 v106, v37, v99
	s_waitcnt lgkmcnt(1)
	v_fmac_f32_e32 v107, v36, v94
	v_fmac_f32_e32 v106, v38, v100
	v_fmac_f32_e32 v107, v37, v95
	v_fmac_f32_e32 v106, v39, v101
	v_fmac_f32_e32 v107, v38, v96
	v_fmac_f32_e32 v107, v39, v97
	ds_read_b128 v[94:97], v89 offset:16544
	ds_read_b128 v[98:101], v89 offset:176
	s_waitcnt lgkmcnt(2)
	v_fmac_f32_e32 v106, v40, v90
	v_fmac_f32_e32 v106, v41, v91
	v_fmac_f32_e32 v106, v42, v92
	v_fmac_f32_e32 v106, v43, v93
	ds_read_b128 v[90:93], v89 offset:16560
	s_waitcnt lgkmcnt(2)
	v_fmac_f32_e32 v107, v40, v94
	v_fmac_f32_e32 v107, v41, v95
	v_fmac_f32_e32 v107, v42, v96
	v_fmac_f32_e32 v107, v43, v97
	s_waitcnt lgkmcnt(1)
	v_fmac_f32_e32 v106, v44, v98
	ds_read_b128 v[94:97], v89 offset:192
	s_waitcnt lgkmcnt(1)
	v_fmac_f32_e32 v107, v44, v90
	v_fmac_f32_e32 v106, v45, v99
	v_fmac_f32_e32 v107, v45, v91
	v_fmac_f32_e32 v106, v46, v100
	v_fmac_f32_e32 v107, v46, v92
	v_fmac_f32_e32 v106, v47, v101
	v_fmac_f32_e32 v107, v47, v93
	ds_read_b128 v[90:93], v89 offset:16576
	ds_read_b128 v[98:101], v89 offset:208
	s_waitcnt lgkmcnt(2)
	v_fmac_f32_e32 v106, v48, v94
	v_fmac_f32_e32 v106, v49, v95
	v_fmac_f32_e32 v106, v50, v96
	s_waitcnt lgkmcnt(1)
	v_fmac_f32_e32 v107, v48, v90
	v_fmac_f32_e32 v107, v49, v91
	v_fmac_f32_e32 v106, v51, v97
	ds_read_b128 v[94:97], v89 offset:16592
	v_fmac_f32_e32 v107, v50, v92
	v_fmac_f32_e32 v107, v51, v93
	ds_read_b128 v[90:93], v89 offset:224
	s_waitcnt lgkmcnt(2)
	v_fmac_f32_e32 v106, v52, v98
	v_fmac_f32_e32 v106, v53, v99
	v_fmac_f32_e32 v106, v54, v100
	v_fmac_f32_e32 v106, v55, v101
	s_waitcnt lgkmcnt(1)
	v_fmac_f32_e32 v107, v52, v94
	v_fmac_f32_e32 v107, v53, v95
	s_waitcnt lgkmcnt(0)
	v_fmac_f32_e32 v106, v56, v90
	v_fmac_f32_e32 v107, v54, v96
	v_fmac_f32_e32 v106, v57, v91
	v_fmac_f32_e32 v107, v55, v97
	ds_read_b128 v[94:97], v89 offset:16608
	ds_read_b128 v[98:101], v89 offset:240
	v_fmac_f32_e32 v106, v58, v92
	v_fmac_f32_e32 v106, v59, v93
	ds_read_b128 v[90:93], v89 offset:16624
	v_cvt_f32_i32_e32 v89, s12
	s_waitcnt lgkmcnt(2)
	v_fmac_f32_e32 v107, v56, v94
	v_fmac_f32_e32 v107, v57, v95
	v_fmac_f32_e32 v107, v58, v96
	v_fmamk_f32 v89, v89, 0xbc44ade8, v81
	v_mul_f32_e64 v89, v82, |v89|
	v_fmac_f32_e32 v107, v59, v97
	v_mul_f32_e32 v89, 0x3fb8aa3b, v89
	s_waitcnt lgkmcnt(0)
	v_fmac_f32_e32 v107, v60, v90
	v_exp_f32_e32 v89, v89
	v_fmac_f32_e32 v106, v60, v98
	v_fmac_f32_e32 v107, v61, v91
	v_fmac_f32_e32 v106, v61, v99
	v_fmac_f32_e32 v107, v62, v92
	v_fmac_f32_e32 v106, v62, v100
	v_fmac_f32_e32 v107, v63, v93
	v_fmac_f32_e32 v106, v63, v101
	v_mul_f32_e32 v94, v89, v107
	v_mul_f32_e32 v91, v89, v106
	v_cndmask_b32_e64 v89, 0, |v94|, vcc
	v_add_f32_e64 v89, |v91|, v89
	s_nop 1
	v_add_f32_dpp v89, v89, v89 quad_perm:[1,0,3,2] row_mask:0xf bank_mask:0xf bound_ctrl:1
	s_nop 1
	v_add_f32_dpp v89, v89, v89 quad_perm:[2,3,0,1] row_mask:0xf bank_mask:0xf bound_ctrl:1
	s_nop 1
	v_add_f32_dpp v89, v89, v89 row_half_mirror row_mask:0xf bank_mask:0xf bound_ctrl:1
	s_nop 1
	v_add_f32_dpp v89, v89, v89 row_mirror row_mask:0xf bank_mask:0xf bound_ctrl:1
	s_nop 1
	v_readlane_b32 s98, v89, 0
	v_readlane_b32 s99, v89, 16
	v_readlane_b32 s100, v89, 32
	v_readlane_b32 s101, v89, 48
	s_nop 1
	v_mov_b32_e32 v90, s98
	v_add_f32_e32 v90, s99, v90
	v_mov_b32_e32 v89, s100
	v_add_f32_e32 v89, s101, v89
	v_add_f32_e32 v89, v89, v90
	s_ashr_i32 s13, s12, 31
	s_lshl_b64 s[0:1], s[12:13], s36
	s_lshl_b64 s[0:1], s[0:1], 2
	s_add_u32 s0, s31, s0
	s_addc_u32 s1, s33, s1
	v_lshl_add_u64 v[92:93], v[68:69], 2, s[0:1]
	global_store_dword v[92:93], v91, off
	v_cndmask_b32_e32 v91, 0, v94, vcc
	v_lshl_add_u64 v[92:93], v[70:71], 2, s[0:1]
	global_store_dword v[92:93], v91, off
	s_and_saveexec_b64 s[14:15], s[2:3]
	s_cbranch_execz .LBB0_92
	s_mov_b64 s[0:1], exec
	s_waitcnt lgkmcnt(0)
	v_mov_b32_e32 v90, v89
	v_bfrev_b32_e32 v89, 1
